# m1 gate-statistics serial loop: LDS reads batched 8 steps per trip
# baseline (speedup 1.0000x reference)
.LBB0_475:
	v_mov_b32_e32 v3, s11
	ds_read_b32 v10, v3
	ds_read_b32 v11, v3 offset:512
	ds_read_b32 v12, v3 offset:4
	ds_read_b32 v13, v3 offset:516
	ds_read_b32 v14, v3 offset:8
	ds_read_b32 v15, v3 offset:520
	ds_read_b32 v16, v3 offset:12
	ds_read_b32 v17, v3 offset:524
	ds_read_b32 v18, v3 offset:16
	ds_read_b32 v19, v3 offset:528
	ds_read_b32 v20, v3 offset:20
	ds_read_b32 v21, v3 offset:532
	ds_read_b32 v22, v3 offset:24
	ds_read_b32 v23, v3 offset:536
	ds_read_b32 v24, v3 offset:28
	ds_read_b32 v25, v3 offset:540
	s_waitcnt lgkmcnt(0)
	s_add_u32 s12, s3, s4
	s_addc_u32 s13, s10, s5
	global_store_dword v1, v2, s[12:13]
	s_add_u32 s12, s8, s4
	v_add_f32_e32 v2, v2, v10
	v_add_f32_e32 v3, v10, v11
	v_max_f32_e32 v3, v2, v3
	s_addc_u32 s13, s9, s5
	v_sub_f32_e32 v2, v2, v3
	s_add_u32 s14, s6, s4
	v_mul_f32_e32 v2, 0x3fb8aa3b, v2
	s_addc_u32 s15, s7, s5
	v_exp_f32_e32 v4, v2
	s_add_u32 s4, s4, 4
	s_addc_u32 s5, s5, 0
	v_mov_b32_e32 v2, v3
	global_store_dword v1, v3, s[12:13]
	global_store_dword v1, v4, s[14:15]
	s_add_u32 s12, s3, s4
	s_addc_u32 s13, s10, s5
	global_store_dword v1, v2, s[12:13]
	s_add_u32 s12, s8, s4
	v_add_f32_e32 v2, v2, v12
	v_add_f32_e32 v3, v12, v13
	v_max_f32_e32 v3, v2, v3
	s_addc_u32 s13, s9, s5
	v_sub_f32_e32 v2, v2, v3
	s_add_u32 s14, s6, s4
	v_mul_f32_e32 v2, 0x3fb8aa3b, v2
	s_addc_u32 s15, s7, s5
	v_exp_f32_e32 v4, v2
	s_add_u32 s4, s4, 4
	s_addc_u32 s5, s5, 0
	v_mov_b32_e32 v2, v3
	global_store_dword v1, v3, s[12:13]
	global_store_dword v1, v4, s[14:15]
	s_add_u32 s12, s3, s4
	s_addc_u32 s13, s10, s5
	global_store_dword v1, v2, s[12:13]
	s_add_u32 s12, s8, s4
	v_add_f32_e32 v2, v2, v14
	v_add_f32_e32 v3, v14, v15
	v_max_f32_e32 v3, v2, v3
	s_addc_u32 s13, s9, s5
	v_sub_f32_e32 v2, v2, v3
	s_add_u32 s14, s6, s4
	v_mul_f32_e32 v2, 0x3fb8aa3b, v2
	s_addc_u32 s15, s7, s5
	v_exp_f32_e32 v4, v2
	s_add_u32 s4, s4, 4
	s_addc_u32 s5, s5, 0
	v_mov_b32_e32 v2, v3
	global_store_dword v1, v3, s[12:13]
	global_store_dword v1, v4, s[14:15]
	s_add_u32 s12, s3, s4
	s_addc_u32 s13, s10, s5
	global_store_dword v1, v2, s[12:13]
	s_add_u32 s12, s8, s4
	v_add_f32_e32 v2, v2, v16
	v_add_f32_e32 v3, v16, v17
	v_max_f32_e32 v3, v2, v3
	s_addc_u32 s13, s9, s5
	v_sub_f32_e32 v2, v2, v3
	s_add_u32 s14, s6, s4
	v_mul_f32_e32 v2, 0x3fb8aa3b, v2
	s_addc_u32 s15, s7, s5
	v_exp_f32_e32 v4, v2
	s_add_u32 s4, s4, 4
	s_addc_u32 s5, s5, 0
	v_mov_b32_e32 v2, v3
	global_store_dword v1, v3, s[12:13]
	global_store_dword v1, v4, s[14:15]
	s_add_u32 s12, s3, s4
	s_addc_u32 s13, s10, s5
	global_store_dword v1, v2, s[12:13]
	s_add_u32 s12, s8, s4
	v_add_f32_e32 v2, v2, v18
	v_add_f32_e32 v3, v18, v19
	v_max_f32_e32 v3, v2, v3
	s_addc_u32 s13, s9, s5
	v_sub_f32_e32 v2, v2, v3
	s_add_u32 s14, s6, s4
	v_mul_f32_e32 v2, 0x3fb8aa3b, v2
	s_addc_u32 s15, s7, s5
	v_exp_f32_e32 v4, v2
	s_add_u32 s4, s4, 4
	s_addc_u32 s5, s5, 0
	v_mov_b32_e32 v2, v3
	global_store_dword v1, v3, s[12:13]
	global_store_dword v1, v4, s[14:15]
	s_add_u32 s12, s3, s4
	s_addc_u32 s13, s10, s5
	global_store_dword v1, v2, s[12:13]
	s_add_u32 s12, s8, s4
	v_add_f32_e32 v2, v2, v20
	v_add_f32_e32 v3, v20, v21
	v_max_f32_e32 v3, v2, v3
	s_addc_u32 s13, s9, s5
	v_sub_f32_e32 v2, v2, v3
	s_add_u32 s14, s6, s4
	v_mul_f32_e32 v2, 0x3fb8aa3b, v2
	s_addc_u32 s15, s7, s5
	v_exp_f32_e32 v4, v2
	s_add_u32 s4, s4, 4
	s_addc_u32 s5, s5, 0
	v_mov_b32_e32 v2, v3
	global_store_dword v1, v3, s[12:13]
	global_store_dword v1, v4, s[14:15]
	s_add_u32 s12, s3, s4
	s_addc_u32 s13, s10, s5
	global_store_dword v1, v2, s[12:13]
	s_add_u32 s12, s8, s4
	v_add_f32_e32 v2, v2, v22
	v_add_f32_e32 v3, v22, v23
	v_max_f32_e32 v3, v2, v3
	s_addc_u32 s13, s9, s5
	v_sub_f32_e32 v2, v2, v3
	s_add_u32 s14, s6, s4
	v_mul_f32_e32 v2, 0x3fb8aa3b, v2
	s_addc_u32 s15, s7, s5
	v_exp_f32_e32 v4, v2
	s_add_u32 s4, s4, 4
	s_addc_u32 s5, s5, 0
	v_mov_b32_e32 v2, v3
	global_store_dword v1, v3, s[12:13]
	global_store_dword v1, v4, s[14:15]
	s_add_u32 s12, s3, s4
	s_addc_u32 s13, s10, s5
	global_store_dword v1, v2, s[12:13]
	s_add_u32 s12, s8, s4
	v_add_f32_e32 v2, v2, v24
	v_add_f32_e32 v3, v24, v25
	v_max_f32_e32 v3, v2, v3
	s_addc_u32 s13, s9, s5
	v_sub_f32_e32 v2, v2, v3
	s_add_u32 s14, s6, s4
	v_mul_f32_e32 v2, 0x3fb8aa3b, v2
	s_addc_u32 s15, s7, s5
	v_exp_f32_e32 v4, v2
	s_add_u32 s4, s4, 4
	s_addc_u32 s5, s5, 0
	v_mov_b32_e32 v2, v3
	global_store_dword v1, v3, s[12:13]
	global_store_dword v1, v4, s[14:15]
	s_add_i32 s11, s11, 32
	s_cmpk_lg_i32 s4, 0x200
	s_cbranch_scc1 .LBB0_475
